# g1 conv section: all q/k/v conv-row loads and gate loads issued at item top into prefetch registers, later loads replaced by register copies
# baseline (speedup 1.0000x reference)
.LBB0_296:
	v_mov_b32_e32 v143, v1
	s_lshl_b32 s0, s86, 1
	s_and_b32 s0, s0, 2
	v_ashrrev_i32_e32 v46, 8, v143
	v_and_b32_e32 v58, 15, v143
	v_add_u32_e32 v62, s0, v46
	v_lshlrev_b32_e32 v141, 3, v58
	v_lshl_or_b32 v56, v62, 7, v141
	v_ashrrev_i32_e32 v57, 31, v56
	s_waitcnt lgkmcnt(0)
	s_bfe_u32 s87, s86, 0x60001
	s_ashr_i32 s89, s86, 7
	s_lshl_b32 s1, s87, 6
	s_lshl_b32 s0, s89, 12
	s_or_b32 s88, s1, s0
	v_and_b32_e32 v130, 0xff, v143
	v_cmp_gt_u32_e32 vcc, 64, v130
	v_or_b32_e32 v130, s88, v130
	v_ashrrev_i32_e32 v131, 31, v130
	v_mov_b32_e32 v132, v62
	v_ashrrev_i32_e32 v133, 31, v62
	v_lshlrev_b64 v[130:131], 5, v[130:131]
	v_lshlrev_b64 v[132:133], 2, v[132:133]
	v_lshl_add_u64 v[130:131], s[22:23], 0, v[130:131]
	v_lshl_add_u64 v[134:135], s[20:21], 0, v[132:133]
	v_lshl_add_u64 v[130:131], v[130:131], 0, v[132:133]
	v_lshl_add_u64 v[132:133], s[14:15], 0, v[132:133]
	s_and_saveexec_b64 s[60:61], vcc
	global_load_dword v126, v[130:131], off
	global_load_dword v127, v[130:131], off offset:16
	global_load_dword v128, v[134:135], off
	global_load_dword v129, v[132:133], off
	s_mov_b64 exec, s[60:61]
	v_lshl_add_u64 v[66:67], v[56:57], 2, s[12:13]
	v_add_co_u32_e32 v68, vcc, s33, v66
	v_lshl_add_u64 v[6:7], v[66:67], 0, s[38:39]
	s_nop 0
	v_addc_co_u32_e32 v69, vcc, 0, v67, vcc
	v_add_co_u32_e32 v14, vcc, 0x3000, v66
	global_load_dwordx4 v[18:21], v[66:67], off offset:16
	global_load_dwordx4 v[2:5], v[66:67], off
	v_addc_co_u32_e32 v15, vcc, 0, v67, vcc
	v_lshl_add_u64 v[8:9], v[66:67], 0, s[40:41]
	global_load_dwordx4 v[22:25], v[6:7], off offset:16
	global_load_dwordx4 v[26:29], v[8:9], off offset:16
	v_add_co_u32_e32 v6, vcc, 0x4000, v66
	v_lshl_add_u64 v[30:31], v[66:67], 0, s[42:43]
	s_nop 0
	v_addc_co_u32_e32 v7, vcc, 0, v67, vcc
	global_load_dwordx4 v[10:13], v[68:69], off offset:2048
	s_nop 0
	global_load_dwordx4 v[6:9], v[6:7], off offset:2048
	s_nop 0
	global_load_dwordx4 v[14:17], v[14:15], off
	s_nop 0
	global_load_dwordx4 v[30:33], v[30:31], off offset:16
	v_bfe_u32 v142, v143, 4, 4
	v_lshlrev_b32_e32 v47, 2, v142
	v_add3_u32 v39, s1, -3, v47
	v_lshl_add_u64 v[48:49], v[56:57], 1, s[8:9]
	v_cmp_lt_i32_e64 s[2:3], -1, v39
	v_cmp_lt_i32_e64 s[4:5], -2, v39
	v_add_u32_e32 v57, s0, v39
	v_add_u32_e32 v40, 1, v39
	v_add_u32_e32 v63, s0, v40
	v_or_b32_e32 v39, 2, v39
	v_add_u32_e32 v61, s0, v39
	v_or_b32_e32 v47, s88, v47
	v_add_u32_e32 v70, 4, v57
	v_add_u32_e32 v224, 5, v57
	v_add_u32_e32 v225, 6, v57
	v_mad_i64_i32 v[146:147], s[90:91], v57, s45, v[48:49]
	v_mad_i64_i32 v[148:149], s[90:91], v63, s45, v[48:49]
	v_mad_i64_i32 v[150:151], s[90:91], v61, s45, v[48:49]
	v_mad_i64_i32 v[64:65], s[90:91], v47, s45, v[48:49]
	v_mad_i64_i32 v[70:71], s[90:91], v70, s45, v[48:49]
	v_mad_i64_i32 v[156:157], s[90:91], v224, s45, v[48:49]
	v_mad_i64_i32 v[158:159], s[90:91], v225, s45, v[48:49]
	v_mov_b32_e32 v34, 0
	v_mov_b32_e32 v35, 0
	v_mov_b32_e32 v36, 0
	v_mov_b32_e32 v37, 0
	v_mov_b32_e32 v42, 0
	v_mov_b32_e32 v43, 0
	v_mov_b32_e32 v44, 0
	v_mov_b32_e32 v45, 0
	v_mov_b32_e32 v38, 0
	v_mov_b32_e32 v39, 0
	v_mov_b32_e32 v40, 0
	v_mov_b32_e32 v41, 0
	v_mov_b64_e32 v[160:161], 0
	v_mov_b64_e32 v[162:163], 0
	v_mov_b64_e32 v[164:165], 0
	v_mov_b64_e32 v[166:167], 0
	v_mov_b64_e32 v[168:169], 0
	v_mov_b64_e32 v[170:171], 0
	v_mov_b64_e32 v[188:189], 0
	v_mov_b64_e32 v[190:191], 0
	v_mov_b64_e32 v[192:193], 0
	v_mov_b64_e32 v[194:195], 0
	v_mov_b64_e32 v[196:197], 0
	v_mov_b64_e32 v[198:199], 0
	s_mov_b64 s[60:61], exec
	s_and_b64 exec, s[60:61], s[2:3]
	global_load_dwordx4 v[34:37], v[146:147], off
	global_load_dwordx4 v[38:41], v[150:151], off
	s_and_b64 exec, s[60:61], s[4:5]
	global_load_dwordx4 v[42:45], v[148:149], off
	s_mov_b64 exec, s[60:61]
	global_load_dwordx4 v[50:53], v[64:65], off
	global_load_dwordx4 v[86:89], v[70:71], off
	global_load_dwordx4 v[216:219], v[156:157], off
	global_load_dwordx4 v[220:223], v[158:159], off
	s_and_b64 exec, s[60:61], s[2:3]
	global_load_dwordx4 v[160:163], v[146:147], off offset:1024
	global_load_dwordx4 v[168:171], v[150:151], off offset:1024
	s_and_b64 exec, s[60:61], s[4:5]
	global_load_dwordx4 v[164:167], v[148:149], off offset:1024
	s_mov_b64 exec, s[60:61]
	global_load_dwordx4 v[172:175], v[64:65], off offset:1024
	global_load_dwordx4 v[176:179], v[70:71], off offset:1024
	global_load_dwordx4 v[180:183], v[156:157], off offset:1024
	global_load_dwordx4 v[184:187], v[158:159], off offset:1024
	s_and_b64 exec, s[60:61], s[2:3]
	global_load_dwordx4 v[188:191], v[146:147], off offset:2048
	global_load_dwordx4 v[196:199], v[150:151], off offset:2048
	s_and_b64 exec, s[60:61], s[4:5]
	global_load_dwordx4 v[192:195], v[148:149], off offset:2048
	s_mov_b64 exec, s[60:61]
	global_load_dwordx4 v[200:203], v[64:65], off offset:2048
	global_load_dwordx4 v[204:207], v[70:71], off offset:2048
	global_load_dwordx4 v[208:211], v[156:157], off offset:2048
	global_load_dwordx4 v[212:215], v[158:159], off offset:2048
	s_waitcnt vmcnt(16)
	v_lshlrev_b32_e32 v54, 16, v37
	v_and_b32_e32 v55, 0xffff0000, v37
	v_mad_i32_i24 v140, v46, s62, 0
	v_lshlrev_b32_e32 v46, 16, v45
	v_and_b32_e32 v47, 0xffff0000, v45
	v_lshlrev_b32_e32 v74, 16, v44
	v_and_b32_e32 v75, 0xffff0000, v44
	v_lshlrev_b32_e32 v80, 16, v39
	v_and_b32_e32 v81, 0xffff0000, v39
	v_lshlrev_b32_e32 v44, 16, v35
	v_and_b32_e32 v45, 0xffff0000, v35
	v_lshlrev_b32_e32 v84, 16, v38
	v_and_b32_e32 v85, 0xffff0000, v38
	v_lshlrev_b32_e32 v38, 16, v34
	v_and_b32_e32 v39, 0xffff0000, v34
	v_pk_fma_f32 v[34:35], v[20:21], v[54:55], 0 op_sel_hi:[1,1,0]
	v_lshlrev_b32_e32 v76, 16, v41
	v_and_b32_e32 v77, 0xffff0000, v41
	v_lshlrev_b32_e32 v78, 16, v40
	v_and_b32_e32 v79, 0xffff0000, v40
	v_lshlrev_b32_e32 v40, 16, v36
	v_and_b32_e32 v41, 0xffff0000, v36
	v_lshlrev_b32_e32 v36, 16, v43
	v_and_b32_e32 v37, 0xffff0000, v43
	v_pk_fma_f32 v[44:45], v[4:5], v[44:45], 0 op_sel_hi:[1,1,0]
	v_pk_fma_f32 v[34:35], v[24:25], v[46:47], v[34:35]
	v_pk_fma_f32 v[44:45], v[12:13], v[36:37], v[44:45]
	v_pk_fma_f32 v[92:93], v[28:29], v[76:77], v[34:35]
	v_and_b32_e32 v102, 64, v137
	v_pk_fma_f32 v[94:95], v[16:17], v[80:81], v[44:45]
	v_xor_b32_e32 v82, 1, v137
	v_add_u32_e32 v118, 64, v102
	v_cmp_lt_i32_e32 vcc, v82, v118
	v_lshlrev_b32_e32 v100, 16, v42
	v_and_b32_e32 v101, 0xffff0000, v42
	v_cndmask_b32_e32 v82, v137, v82, vcc
	v_lshlrev_b32_e32 v103, 2, v82
	v_pk_fma_f32 v[54:55], v[2:3], v[38:39], 0 op_sel_hi:[1,1,0]
	v_pk_fma_f32 v[46:47], v[20:21], v[46:47], 0 op_sel_hi:[1,1,0]
	v_pk_fma_f32 v[54:55], v[10:11], v[100:101], v[54:55]
	v_pk_fma_f32 v[46:47], v[24:25], v[76:77], v[46:47]
	v_pk_fma_f32 v[54:55], v[14:15], v[84:85], v[54:55]
	v_pk_fma_f32 v[42:43], v[18:19], v[40:41], 0 op_sel_hi:[1,1,0]
	v_pk_fma_f32 v[36:37], v[4:5], v[36:37], 0 op_sel_hi:[1,1,0]
	v_pk_fma_f32 v[42:43], v[22:23], v[74:75], v[42:43]
	v_pk_fma_f32 v[36:37], v[12:13], v[80:81], v[36:37]
	v_pk_fma_f32 v[42:43], v[26:27], v[78:79], v[42:43]
	v_add_u32_e32 v72, 5, v57
	v_mad_i64_i32 v[72:73], s[0:1], v72, s45, v[48:49]
	v_pk_fma_f32 v[80:81], v[4:5], v[80:81], 0 op_sel_hi:[1,1,0]
	v_lshlrev_b32_e32 v90, 16, v53
	v_and_b32_e32 v91, 0xffff0000, v53
	v_lshlrev_b32_e32 v44, 16, v51
	v_and_b32_e32 v45, 0xffff0000, v51
	v_lshlrev_b32_e32 v34, 16, v50
	v_and_b32_e32 v35, 0xffff0000, v50
	v_pk_fma_f32 v[50:51], v[32:33], v[90:91], v[92:93]
	v_lshlrev_b32_e32 v82, 16, v52
	v_mul_f32_e32 v92, 0xbfb8aa3b, v50
	v_mul_f32_e32 v93, 0xbfb8aa3b, v51
	v_exp_f32_e32 v92, v92
	v_exp_f32_e32 v93, v93
	v_and_b32_e32 v83, 0xffff0000, v52
	v_pk_fma_f32 v[52:53], v[8:9], v[44:45], v[94:95]
	v_add_f32_e32 v92, 1.0, v92
	v_mul_f32_e32 v96, 0xbfb8aa3b, v52
	v_mul_f32_e32 v97, 0xbfb8aa3b, v53
	v_exp_f32_e32 v96, v96
	v_exp_f32_e32 v97, v97
	v_add_f32_e32 v93, 1.0, v93
	v_rcp_f32_e32 v92, v92
	v_rcp_f32_e32 v93, v93
	v_pk_fma_f32 v[54:55], v[6:7], v[34:35], v[54:55]
	v_add_f32_e32 v96, 1.0, v96
	v_add_f32_e32 v97, 1.0, v97
	v_mul_f32_e32 v98, 0xbfb8aa3b, v54
	v_rcp_f32_e32 v96, v96
	v_rcp_f32_e32 v97, v97
	v_pk_mul_f32 v[112:113], v[50:51], v[92:93]
	v_mul_f32_e32 v51, 0xbfb8aa3b, v55
	v_exp_f32_e32 v50, v98
	v_exp_f32_e32 v51, v51
	v_lshlrev_b32_e32 v98, 16, v89
	v_and_b32_e32 v99, 0xffff0000, v89
	v_pk_fma_f32 v[46:47], v[28:29], v[90:91], v[46:47]
	v_pk_mul_f32 v[114:115], v[52:53], v[96:97]
	v_pk_fma_f32 v[46:47], v[32:33], v[98:99], v[46:47]
	v_add_f32_e32 v50, 1.0, v50
	v_mul_f32_e32 v52, 0xbfb8aa3b, v46
	v_mul_f32_e32 v53, 0xbfb8aa3b, v47
	v_add_f32_e32 v51, 1.0, v51
	v_exp_f32_e32 v52, v52
	v_exp_f32_e32 v53, v53
	v_pk_fma_f32 v[42:43], v[30:31], v[82:83], v[42:43]
	v_rcp_f32_e32 v50, v50
	v_rcp_f32_e32 v51, v51
	v_mul_f32_e32 v94, 0xbfb8aa3b, v42
	v_mul_f32_e32 v95, 0xbfb8aa3b, v43
	v_exp_f32_e32 v94, v94
	v_exp_f32_e32 v95, v95
	v_add_f32_e32 v52, 1.0, v52
	v_add_f32_e32 v53, 1.0, v53
	v_rcp_f32_e32 v52, v52
	v_rcp_f32_e32 v53, v53
	v_pk_mul_f32 v[116:117], v[54:55], v[50:51]
	v_pk_fma_f32 v[50:51], v[18:19], v[74:75], 0 op_sel_hi:[1,1,0]
	v_add_f32_e32 v94, 1.0, v94
	v_pk_fma_f32 v[50:51], v[22:23], v[78:79], v[50:51]
	v_add_f32_e32 v95, 1.0, v95
	v_lshlrev_b32_e32 v96, 16, v88
	v_and_b32_e32 v97, 0xffff0000, v88
	v_pk_fma_f32 v[50:51], v[26:27], v[82:83], v[50:51]
	v_rcp_f32_e32 v94, v94
	v_rcp_f32_e32 v95, v95
	v_pk_fma_f32 v[50:51], v[30:31], v[96:97], v[50:51]
	v_pk_mul_f32 v[46:47], v[46:47], v[52:53]
	v_mul_f32_e32 v52, 0xbfb8aa3b, v50
	v_mul_f32_e32 v53, 0xbfb8aa3b, v51
	v_exp_f32_e32 v52, v52
	v_exp_f32_e32 v53, v53
	v_pk_mul_f32 v[42:43], v[42:43], v[94:95]
	v_lshlrev_b32_e32 v94, 16, v87
	v_and_b32_e32 v95, 0xffff0000, v87
	v_pk_fma_f32 v[36:37], v[16:17], v[44:45], v[36:37]
	v_add_f32_e32 v52, 1.0, v52
	v_pk_fma_f32 v[36:37], v[8:9], v[94:95], v[36:37]
	v_add_f32_e32 v53, 1.0, v53
	v_mul_f32_e32 v54, 0xbfb8aa3b, v36
	v_mul_f32_e32 v55, 0xbfb8aa3b, v37
	v_rcp_f32_e32 v52, v52
	v_rcp_f32_e32 v53, v53
	v_exp_f32_e32 v54, v54
	v_exp_f32_e32 v55, v55
	v_lshlrev_b32_e32 v92, 16, v86
	v_pk_mul_f32 v[50:51], v[50:51], v[52:53]
	v_add_f32_e32 v52, 1.0, v54
	v_add_f32_e32 v53, 1.0, v55
	v_pk_fma_f32 v[54:55], v[2:3], v[100:101], 0 op_sel_hi:[1,1,0]
	v_and_b32_e32 v93, 0xffff0000, v86
	v_pk_fma_f32 v[54:55], v[10:11], v[84:85], v[54:55]
	v_rcp_f32_e32 v52, v52
	v_pk_fma_f32 v[54:55], v[14:15], v[34:35], v[54:55]
	v_rcp_f32_e32 v53, v53
	v_pk_fma_f32 v[54:55], v[6:7], v[92:93], v[54:55]
	v_pk_mul_f32 v[110:111], v[116:117], v[116:117]
	v_mul_f32_e32 v86, 0xbfb8aa3b, v54
	v_mul_f32_e32 v87, 0xbfb8aa3b, v55
	v_exp_f32_e32 v86, v86
	v_exp_f32_e32 v87, v87
	v_pk_mul_f32 v[52:53], v[36:37], v[52:53]
	v_pk_mul_f32 v[108:109], v[114:115], v[114:115]
	v_add_f32_e32 v86, 1.0, v86
	v_add_f32_e32 v87, 1.0, v87
	v_rcp_f32_e32 v86, v86
	v_rcp_f32_e32 v87, v87
	v_pk_mul_f32 v[36:37], v[52:53], v[52:53]
	v_mov_b32_e32 v101, v110
	v_pk_mul_f32 v[106:107], v[42:43], v[42:43]
	v_pk_mul_f32 v[54:55], v[54:55], v[86:87]
	v_pk_mul_f32 v[88:89], v[50:51], v[50:51]
	v_pk_mul_f32 v[86:87], v[54:55], v[54:55]
	v_pk_mul_f32 v[104:105], v[112:113], v[112:113]
	v_mov_b32_e32 v100, v86
	v_mov_b32_e32 v110, v87
	v_pk_add_f32 v[86:87], v[100:101], v[110:111]
	v_mov_b32_e32 v100, v36
	v_mov_b32_e32 v101, v108
	v_pk_add_f32 v[86:87], v[100:101], v[86:87]
	v_mov_b32_e32 v108, v37
	v_pk_add_f32 v[36:37], v[108:109], v[86:87]
	v_mov_b32_e32 v86, v88
	v_mov_b32_e32 v87, v106
	v_pk_mul_f32 v[74:75], v[46:47], v[46:47]
	v_pk_add_f32 v[36:37], v[86:87], v[36:37]
	v_mov_b32_e32 v106, v89
	v_pk_add_f32 v[36:37], v[106:107], v[36:37]
	v_mov_b32_e32 v86, v74
	v_mov_b32_e32 v87, v104
	v_pk_add_f32 v[36:37], v[86:87], v[36:37]
	v_mov_b32_e32 v104, v75
	v_pk_add_f32 v[36:37], v[104:105], v[36:37]
	ds_bpermute_b32 v75, v103, v37
	ds_bpermute_b32 v74, v103, v36
	v_xor_b32_e32 v86, 2, v137
	v_cmp_lt_i32_e32 vcc, v86, v118
	v_pk_fma_f32 v[80:81], v[12:13], v[44:45], v[80:81]
	v_pk_fma_f32 v[4:5], v[4:5], v[44:45], 0 op_sel_hi:[1,1,0]
	v_cndmask_b32_e32 v86, v137, v86, vcc
	v_lshlrev_b32_e32 v104, 2, v86
	s_waitcnt lgkmcnt(0)
	v_pk_add_f32 v[36:37], v[36:37], v[74:75]
	ds_bpermute_b32 v75, v104, v37
	ds_bpermute_b32 v74, v104, v36
	v_xor_b32_e32 v86, 4, v137
	v_cmp_lt_i32_e32 vcc, v86, v118
	v_pk_fma_f32 v[80:81], v[16:17], v[94:95], v[80:81]
	v_pk_fma_f32 v[4:5], v[12:13], v[94:95], v[4:5]
	v_cndmask_b32_e32 v86, v137, v86, vcc
	v_lshlrev_b32_e32 v105, 2, v86
	s_waitcnt lgkmcnt(0)
	v_pk_add_f32 v[36:37], v[36:37], v[74:75]
	ds_bpermute_b32 v75, v105, v37
	ds_bpermute_b32 v74, v105, v36
	v_xor_b32_e32 v86, 8, v137
	v_cmp_lt_i32_e32 vcc, v86, v118
	v_lshl_add_u32 v107, v141, 1, v140
	v_mad_u32_u24 v122, v142, s64, v107
	s_waitcnt lgkmcnt(0)
	v_pk_add_f32 v[36:37], v[36:37], v[74:75]
	v_add_u32_e32 v74, 6, v57
	v_mad_i64_i32 v[74:75], s[0:1], v74, s45, v[48:49]
	v_cndmask_b32_e32 v86, v137, v86, vcc
	v_lshlrev_b32_e32 v106, 2, v86
	ds_bpermute_b32 v87, v106, v37
	ds_bpermute_b32 v86, v106, v36
	s_waitcnt lgkmcnt(0)
	v_pk_add_f32 v[36:37], v[36:37], v[86:87]
	s_nop 0
	v_pk_add_f32 v[48:49], v[36:37], s[44:45] op_sel_hi:[1,0]
	s_waitcnt vmcnt(14)
	v_mov_b64_e32 v[38:39], v[216:217]
	v_mov_b64_e32 v[40:41], v[218:219]
	v_mov_b64_e32 v[108:109], v[220:221]
	v_mov_b64_e32 v[110:111], v[222:223]
	v_lshlrev_b32_e32 v12, 16, v109
	v_mul_f32_e32 v36, 0x4b800000, v49
	v_cmp_gt_f32_e32 vcc, s65, v49
	v_and_b32_e32 v13, 0xffff0000, v109
	s_nop 0
	v_cndmask_b32_e32 v36, v49, v36, vcc
	v_rsq_f32_e32 v37, v36
	v_mov_b32_e32 v36, 0
	v_mul_f32_e32 v49, 0x45800000, v37
	v_cndmask_b32_e32 v37, v37, v49, vcc
	v_mul_f32_e32 v88, 0x3db504f3, v37
	v_pk_mul_f32 v[86:87], v[42:43], v[88:89] op_sel_hi:[1,0]
	v_pk_fma_f32 v[42:43], v[20:21], v[76:77], 0 op_sel_hi:[1,1,0]
	v_pk_mul_f32 v[100:101], v[116:117], v[88:89] op_sel_hi:[1,0]
	v_pk_fma_f32 v[42:43], v[24:25], v[90:91], v[42:43]
	v_pk_mul_f32 v[114:115], v[114:115], v[88:89] op_sel_hi:[1,0]
	v_pk_mul_f32 v[88:89], v[112:113], v[88:89] op_sel_hi:[1,0]
	v_lshlrev_b32_e32 v112, 16, v41
	v_and_b32_e32 v113, 0xffff0000, v41
	v_pk_fma_f32 v[42:43], v[28:29], v[98:99], v[42:43]
	v_lshlrev_b32_e32 v116, 16, v40
	v_pk_fma_f32 v[76:77], v[32:33], v[112:113], v[42:43]
	v_cvt_pk_bf16_f32 v42, v100, v101
	v_mul_f32_e32 v37, 0xbfb8aa3b, v76
	v_exp_f32_e32 v37, v37
	v_mul_f32_e32 v41, 0xbfb8aa3b, v77
	v_exp_f32_e32 v41, v41
	v_and_b32_e32 v117, 0xffff0000, v40
	v_add_f32_e32 v37, 1.0, v37
	v_rcp_f32_e32 v100, v37
	v_add_f32_e32 v37, 1.0, v41
	v_pk_fma_f32 v[40:41], v[18:19], v[78:79], 0 op_sel_hi:[1,1,0]
	v_rcp_f32_e32 v101, v37
	v_pk_fma_f32 v[40:41], v[22:23], v[82:83], v[40:41]
	v_cvt_pk_bf16_f32 v43, v114, v115
	v_pk_fma_f32 v[40:41], v[26:27], v[96:97], v[40:41]
	v_lshlrev_b32_e32 v114, 16, v39
	v_pk_fma_f32 v[118:119], v[30:31], v[116:117], v[40:41]
	v_and_b32_e32 v115, 0xffff0000, v39
	v_mul_f32_e32 v40, 0xbfb8aa3b, v118
	v_exp_f32_e32 v40, v40
	v_mul_f32_e32 v41, 0xbfb8aa3b, v119
	v_exp_f32_e32 v41, v41
	v_pk_fma_f32 v[80:81], v[8:9], v[114:115], v[80:81]
	v_add_f32_e32 v37, 1.0, v40
	v_rcp_f32_e32 v120, v37
	v_add_f32_e32 v37, 1.0, v41
	v_rcp_f32_e32 v121, v37
	v_mul_f32_e32 v37, 0xbfb8aa3b, v80
	v_exp_f32_e32 v37, v37
	v_mul_f32_e32 v39, 0xbfb8aa3b, v81
	v_exp_f32_e32 v39, v39
	v_pk_mul_f32 v[40:41], v[76:77], v[100:101]
	v_add_f32_e32 v37, 1.0, v37
	v_pk_mul_f32 v[76:77], v[118:119], v[120:121]
	v_rcp_f32_e32 v118, v37
	v_add_f32_e32 v37, 1.0, v39
	v_lshlrev_b32_e32 v120, 16, v38
	v_and_b32_e32 v121, 0xffff0000, v38
	v_pk_fma_f32 v[38:39], v[2:3], v[84:85], 0 op_sel_hi:[1,1,0]
	v_pk_fma_f32 v[20:21], v[20:21], v[90:91], 0 op_sel_hi:[1,1,0]
	v_pk_fma_f32 v[38:39], v[10:11], v[34:35], v[38:39]
	v_pk_fma_f32 v[20:21], v[24:25], v[98:99], v[20:21]
	v_pk_fma_f32 v[38:39], v[14:15], v[92:93], v[38:39]
	v_pk_fma_f32 v[20:21], v[28:29], v[112:113], v[20:21]
	v_pk_fma_f32 v[84:85], v[6:7], v[120:121], v[38:39]
	v_lshlrev_b32_e32 v24, 16, v111
	v_and_b32_e32 v25, 0xffff0000, v111
	v_rcp_f32_e32 v119, v37
	v_mul_f32_e32 v37, 0xbfb8aa3b, v84
	v_pk_fma_f32 v[20:21], v[32:33], v[24:25], v[20:21]
	v_exp_f32_e32 v37, v37
	v_mul_f32_e32 v38, 0xbfb8aa3b, v85
	v_mul_f32_e32 v24, 0xbfb8aa3b, v20
	v_mul_f32_e32 v25, 0xbfb8aa3b, v21
	v_exp_f32_e32 v49, v38
	v_exp_f32_e32 v24, v24
	v_exp_f32_e32 v25, v25
	v_pk_fma_f32 v[2:3], v[2:3], v[34:35], 0 op_sel_hi:[1,1,0]
	v_add_f32_e32 v37, 1.0, v37
	v_pk_fma_f32 v[2:3], v[10:11], v[92:93], v[2:3]
	v_lshlrev_b32_e32 v10, 16, v108
	v_pk_fma_f32 v[2:3], v[14:15], v[120:121], v[2:3]
	v_and_b32_e32 v11, 0xffff0000, v108
	v_pk_mul_f32 v[38:39], v[80:81], v[118:119]
	v_rcp_f32_e32 v80, v37
	v_add_f32_e32 v37, 1.0, v49
	v_add_f32_e32 v24, 1.0, v24
	v_add_f32_e32 v25, 1.0, v25
	v_pk_fma_f32 v[4:5], v[16:17], v[114:115], v[4:5]
	v_pk_fma_f32 v[2:3], v[6:7], v[10:11], v[2:3]
	v_rcp_f32_e32 v81, v37
	v_rcp_f32_e32 v24, v24
	v_rcp_f32_e32 v25, v25
	v_pk_fma_f32 v[4:5], v[8:9], v[12:13], v[4:5]
	v_mul_f32_e32 v6, 0xbfb8aa3b, v2
	v_mul_f32_e32 v7, 0xbfb8aa3b, v3
	v_mul_f32_e32 v8, 0xbfb8aa3b, v4
	v_mul_f32_e32 v9, 0xbfb8aa3b, v5
	v_exp_f32_e32 v6, v6
	v_exp_f32_e32 v7, v7
	v_pk_fma_f32 v[18:19], v[18:19], v[82:83], 0 op_sel_hi:[1,1,0]
	v_exp_f32_e32 v8, v8
	v_exp_f32_e32 v9, v9
	v_pk_fma_f32 v[18:19], v[22:23], v[96:97], v[18:19]
	v_pk_mul_f32 v[84:85], v[84:85], v[80:81]
	v_pk_mul_f32 v[80:81], v[20:21], v[24:25]
	v_pk_fma_f32 v[18:19], v[26:27], v[116:117], v[18:19]
	v_lshlrev_b32_e32 v20, 16, v110
	v_and_b32_e32 v21, 0xffff0000, v110
	v_pk_fma_f32 v[18:19], v[30:31], v[20:21], v[18:19]
	v_add_f32_e32 v6, 1.0, v6
	v_add_f32_e32 v7, 1.0, v7
	v_mul_f32_e32 v20, 0xbfb8aa3b, v18
	v_mul_f32_e32 v21, 0xbfb8aa3b, v19
	v_add_f32_e32 v8, 1.0, v8
	v_add_f32_e32 v9, 1.0, v9
	v_rcp_f32_e32 v6, v6
	v_rcp_f32_e32 v7, v7
	v_exp_f32_e32 v20, v20
	v_exp_f32_e32 v21, v21
	v_rcp_f32_e32 v8, v8
	v_rcp_f32_e32 v9, v9
	v_pk_mul_f32 v[2:3], v[2:3], v[6:7]
	v_pk_mul_f32 v[32:33], v[84:85], v[84:85]
	v_add_f32_e32 v20, 1.0, v20
	v_add_f32_e32 v21, 1.0, v21
	v_pk_mul_f32 v[92:93], v[4:5], v[8:9]
	v_pk_mul_f32 v[6:7], v[2:3], v[2:3]
	v_pk_mul_f32 v[28:29], v[38:39], v[38:39]
	v_rcp_f32_e32 v20, v20
	v_rcp_f32_e32 v21, v21
	v_pk_mul_f32 v[4:5], v[92:93], v[92:93]
	v_mov_b32_e32 v8, v6
	v_mov_b32_e32 v9, v32
	v_mov_b32_e32 v32, v7
	v_pk_add_f32 v[6:7], v[8:9], v[32:33]
	v_mov_b32_e32 v8, v4
	v_mov_b32_e32 v9, v28
	v_pk_add_f32 v[6:7], v[8:9], v[6:7]
	v_add_co_u32_e32 v8, vcc, 0x2000, v66
	v_mov_b32_e32 v28, v5
	v_lshl_add_u64 v[12:13], v[66:67], 0, s[46:47]
	v_addc_co_u32_e32 v9, vcc, 0, v67, vcc
	v_pk_mul_f32 v[90:91], v[18:19], v[20:21]
	v_pk_add_f32 v[94:95], v[28:29], v[6:7]
	global_load_dwordx4 v[20:23], v[66:67], off offset:2064
	global_load_dwordx4 v[4:7], v[66:67], off offset:2048
	s_nop 0
	global_load_dwordx4 v[8:11], v[8:9], off
	s_nop 0
	global_load_dwordx4 v[24:27], v[12:13], off offset:16
	v_add_co_u32_e32 v12, vcc, 0x3000, v66
	v_lshl_add_u64 v[16:17], v[66:67], 0, s[48:49]
	s_nop 0
	v_addc_co_u32_e32 v13, vcc, 0, v67, vcc
	global_load_dwordx4 v[12:15], v[12:13], off offset:2048
	s_nop 0
	global_load_dwordx4 v[28:31], v[16:17], off offset:16
	v_add_co_u32_e32 v16, vcc, 0x5000, v66
	v_lshl_add_u64 v[32:33], v[66:67], 0, s[50:51]
	s_nop 0
	v_addc_co_u32_e32 v17, vcc, 0, v67, vcc
	global_load_dwordx4 v[16:19], v[16:17], off
	s_nop 0
	global_load_dwordx4 v[32:35], v[32:33], off offset:16
	v_pk_mul_f32 v[100:101], v[76:77], v[76:77]
	v_pk_mul_f32 v[44:45], v[90:91], v[90:91]
	v_mov_b32_e32 v97, v100
	v_mov_b32_e32 v96, v44
	v_pk_mul_f32 v[78:79], v[40:41], v[40:41]
	v_pk_mul_f32 v[82:83], v[80:81], v[80:81]
	v_pk_add_f32 v[94:95], v[96:97], v[94:95]
	v_mov_b32_e32 v100, v45
	v_pk_add_f32 v[44:45], v[100:101], v[94:95]
	v_mov_b32_e32 v94, v82
	v_mov_b32_e32 v95, v78
	v_pk_add_f32 v[44:45], v[94:95], v[44:45]
	v_mov_b32_e32 v78, v83
	v_pk_add_f32 v[44:45], v[78:79], v[44:45]
	ds_bpermute_b32 v79, v103, v45
	ds_bpermute_b32 v78, v103, v44
	v_mul_f32_e32 v37, 0x4b800000, v48
	v_cmp_gt_f32_e32 vcc, s65, v48
	s_nop 1
	v_cndmask_b32_e32 v37, v48, v37, vcc
	s_waitcnt lgkmcnt(0)
	v_pk_add_f32 v[48:49], v[44:45], v[78:79]
	ds_bpermute_b32 v79, v104, v49
	ds_bpermute_b32 v78, v104, v48
	v_cvt_pk_bf16_f32 v44, v86, v87
	v_cvt_pk_bf16_f32 v45, v88, v89
	ds_write_b128 v122, v[42:45] offset:17408
	v_rsq_f32_e32 v37, v37
	s_waitcnt lgkmcnt(1)
	v_pk_add_f32 v[42:43], v[48:49], v[78:79]
	ds_bpermute_b32 v45, v105, v43
	ds_bpermute_b32 v44, v105, v42
	v_mul_f32_e32 v82, 0x45800000, v37
	v_cndmask_b32_e32 v37, v37, v82, vcc
	v_mul_f32_e32 v48, 0x3db504f3, v37
	v_pk_mul_f32 v[54:55], v[54:55], v[48:49] op_sel_hi:[1,0]
	s_waitcnt lgkmcnt(0)
	v_pk_add_f32 v[44:45], v[42:43], v[44:45]
	ds_bpermute_b32 v79, v106, v45
	ds_bpermute_b32 v78, v106, v44
	v_pk_mul_f32 v[52:53], v[52:53], v[48:49] op_sel_hi:[1,0]
	v_pk_mul_f32 v[50:51], v[50:51], v[48:49] op_sel_hi:[1,0]
	v_pk_mul_f32 v[46:47], v[46:47], v[48:49] op_sel_hi:[1,0]
	v_cvt_pk_bf16_f32 v42, v54, v55
	s_waitcnt lgkmcnt(0)
	v_pk_add_f32 v[44:45], v[44:45], v[78:79]
	v_cvt_pk_bf16_f32 v43, v52, v53
	v_pk_add_f32 v[48:49], v[44:45], s[44:45] op_sel_hi:[1,0]
	v_cvt_pk_bf16_f32 v44, v50, v51
	v_mul_f32_e32 v37, 0x4b800000, v49
	v_cmp_gt_f32_e32 vcc, s65, v49
	v_cvt_pk_bf16_f32 v45, v46, v47
	ds_write_b128 v122, v[42:45] offset:17680
	v_cndmask_b32_e32 v37, v49, v37, vcc
	v_rsq_f32_e32 v37, v37
	v_mov_b32_e32 v49, 0
	v_mul_f32_e32 v42, 0x45800000, v37
	v_cndmask_b32_e32 v37, v37, v42, vcc
	v_mul_f32_e32 v42, 0x3db504f3, v37
	v_mul_f32_e32 v37, 0x4b800000, v48
	v_cmp_gt_f32_e32 vcc, s65, v48
	v_pk_mul_f32 v[44:45], v[84:85], v[42:43] op_sel_hi:[1,0]
	v_pk_mul_f32 v[46:47], v[38:39], v[42:43] op_sel_hi:[1,0]
	v_cndmask_b32_e32 v37, v48, v37, vcc
	v_rsq_f32_e32 v37, v37
	v_pk_mul_f32 v[50:51], v[76:77], v[42:43] op_sel_hi:[1,0]
	v_pk_mul_f32 v[42:43], v[40:41], v[42:43] op_sel_hi:[1,0]
	v_cvt_pk_bf16_f32 v38, v44, v45
	v_cvt_pk_bf16_f32 v39, v46, v47
	v_cvt_pk_bf16_f32 v40, v50, v51
	v_cvt_pk_bf16_f32 v41, v42, v43
	ds_write_b128 v122, v[38:41] offset:17952
	v_mul_f32_e32 v38, 0x45800000, v37
	v_cndmask_b32_e32 v37, v37, v38, vcc
	v_mul_f32_e32 v38, 0x3db504f3, v37
	v_pk_mul_f32 v[2:3], v[2:3], v[38:39] op_sel_hi:[1,0]
	v_pk_mul_f32 v[40:41], v[92:93], v[38:39] op_sel_hi:[1,0]
	v_pk_mul_f32 v[42:43], v[90:91], v[38:39] op_sel_hi:[1,0]
	v_pk_mul_f32 v[44:45], v[80:81], v[38:39] op_sel_hi:[1,0]
	v_cvt_pk_bf16_f32 v38, v2, v3
	v_cvt_pk_bf16_f32 v39, v40, v41
	v_cvt_pk_bf16_f32 v40, v42, v43
	v_cvt_pk_bf16_f32 v41, v44, v45
	ds_write_b128 v122, v[38:41] offset:18224
	v_add_u32_e32 v40, 0x200, v56
	v_ashrrev_i32_e32 v41, 31, v40
	v_mov_b32_e32 v48, 0
	v_mov_b32_e32 v50, 0
	v_mov_b32_e32 v51, 0
	s_and_saveexec_b64 s[60:61], s[2:3]
	s_cbranch_execz .LBB0_304
	v_mov_b64_e32 v[2:3], s[8:9]
	v_mad_i64_i32 v[2:3], s[0:1], v57, s45, v[2:3]
	v_lshl_add_u64 v[2:3], v[40:41], 1, v[2:3]
.LBB0_304:
	s_or_b64 exec, exec, s[60:61]
	v_mov_b32_e32 v37, 0
	v_mov_b32_e32 v38, 0
	v_mov_b32_e32 v39, 0
	s_and_saveexec_b64 s[60:61], s[4:5]
	s_cbranch_execz .LBB0_306
	v_mov_b64_e32 v[2:3], s[8:9]
	v_mad_i64_i32 v[2:3], s[0:1], v63, s45, v[2:3]
	v_lshl_add_u64 v[2:3], v[40:41], 1, v[2:3]
.LBB0_306:
	s_or_b64 exec, exec, s[60:61]
	v_mov_b32_e32 v2, 0
	v_mov_b32_e32 v52, 0
	v_mov_b32_e32 v53, 0
	v_mov_b32_e32 v54, 0
	v_mov_b32_e32 v55, 0
	s_and_saveexec_b64 s[60:61], s[2:3]
	s_cbranch_execz .LBB0_308
	v_mov_b64_e32 v[42:43], s[8:9]
	v_mad_i64_i32 v[42:43], s[0:1], v61, s45, v[42:43]
	v_lshl_add_u64 v[40:41], v[40:41], 1, v[42:43]
.LBB0_308:
	s_or_b64 exec, exec, s[60:61]
	s_waitcnt vmcnt(0)
	v_mov_b64_e32 v[48:49], v[160:161]
	v_mov_b64_e32 v[50:51], v[162:163]
	v_mov_b64_e32 v[36:37], v[164:165]
	v_mov_b64_e32 v[38:39], v[166:167]
	v_mov_b64_e32 v[52:53], v[168:169]
	v_mov_b64_e32 v[54:55], v[170:171]
	v_mov_b64_e32 v[82:83], v[172:173]
	v_mov_b64_e32 v[84:85], v[174:175]
	v_mov_b64_e32 v[44:45], v[176:177]
	v_mov_b64_e32 v[46:47], v[178:179]
	v_mov_b64_e32 v[40:41], v[180:181]
	v_mov_b64_e32 v[42:43], v[182:183]
	v_lshlrev_b32_e32 v90, 16, v51
	v_and_b32_e32 v91, 0xffff0000, v51
	v_lshlrev_b32_e32 v88, 16, v39
	v_and_b32_e32 v89, 0xffff0000, v39
	v_lshlrev_b32_e32 v76, 16, v55
	v_and_b32_e32 v77, 0xffff0000, v55
	v_lshlrev_b32_e32 v94, 16, v38
	v_and_b32_e32 v95, 0xffff0000, v38
	v_lshlrev_b32_e32 v78, 16, v54
	v_and_b32_e32 v79, 0xffff0000, v54
	v_lshlrev_b32_e32 v38, 16, v50
	v_and_b32_e32 v39, 0xffff0000, v50
	v_lshlrev_b32_e32 v50, 16, v37
	v_and_b32_e32 v51, 0xffff0000, v37
	v_lshlrev_b32_e32 v54, 16, v49
	v_and_b32_e32 v55, 0xffff0000, v49
	v_lshlrev_b32_e32 v100, 16, v36
	v_and_b32_e32 v101, 0xffff0000, v36
	v_lshlrev_b32_e32 v36, 16, v48
	v_and_b32_e32 v37, 0xffff0000, v48
	v_pk_fma_f32 v[48:49], v[22:23], v[90:91], 0 op_sel_hi:[1,1,0]
	v_pk_fma_f32 v[38:39], v[20:21], v[38:39], 0 op_sel_hi:[1,1,0]
	v_pk_fma_f32 v[48:49], v[26:27], v[88:89], v[48:49]
	v_lshlrev_b32_e32 v80, 16, v53
	v_and_b32_e32 v81, 0xffff0000, v53
	v_lshlrev_b32_e32 v86, 16, v52
	v_and_b32_e32 v87, 0xffff0000, v52
	v_pk_fma_f32 v[52:53], v[6:7], v[54:55], 0 op_sel_hi:[1,1,0]
	v_pk_fma_f32 v[38:39], v[24:25], v[94:95], v[38:39]
	v_pk_fma_f32 v[48:49], v[30:31], v[76:77], v[48:49]
	v_pk_fma_f32 v[36:37], v[4:5], v[36:37], 0 op_sel_hi:[1,1,0]
	v_pk_fma_f32 v[54:55], v[22:23], v[88:89], 0 op_sel_hi:[1,1,0]
	v_pk_fma_f32 v[52:53], v[10:11], v[50:51], v[52:53]
	v_pk_fma_f32 v[38:39], v[28:29], v[78:79], v[38:39]
	v_pk_fma_f32 v[36:37], v[8:9], v[100:101], v[36:37]
	v_pk_fma_f32 v[96:97], v[26:27], v[76:77], v[54:55]
	v_pk_fma_f32 v[52:53], v[14:15], v[80:81], v[52:53]
	v_pk_fma_f32 v[98:99], v[12:13], v[86:87], v[36:37]
	v_pk_fma_f32 v[50:51], v[6:7], v[50:51], 0 op_sel_hi:[1,1,0]
	s_waitcnt vmcnt(2)
	v_lshlrev_b32_e32 v90, 16, v85
	v_and_b32_e32 v91, 0xffff0000, v85
	v_lshlrev_b32_e32 v88, 16, v84
	v_and_b32_e32 v89, 0xffff0000, v84
	v_pk_fma_f32 v[48:49], v[34:35], v[90:91], v[48:49]
	v_lshlrev_b32_e32 v54, 16, v83
	v_and_b32_e32 v55, 0xffff0000, v83
	s_waitcnt vmcnt(1)
	v_lshlrev_b32_e32 v92, 16, v47
	v_and_b32_e32 v93, 0xffff0000, v47
	v_pk_fma_f32 v[38:39], v[32:33], v[88:89], v[38:39]
	v_mul_f32_e32 v3, 0xbfb8aa3b, v48
	v_mul_f32_e32 v47, 0xbfb8aa3b, v49
	v_lshlrev_b32_e32 v36, 16, v82
	v_and_b32_e32 v37, 0xffff0000, v82
	v_pk_fma_f32 v[52:53], v[18:19], v[54:55], v[52:53]
	v_pk_fma_f32 v[84:85], v[30:31], v[90:91], v[96:97]
	v_mul_f32_e32 v96, 0xbfb8aa3b, v38
	v_mul_f32_e32 v97, 0xbfb8aa3b, v39
	v_exp_f32_e32 v3, v3
	v_exp_f32_e32 v47, v47
	v_pk_fma_f32 v[82:83], v[16:17], v[36:37], v[98:99]
	v_mul_f32_e32 v98, 0xbfb8aa3b, v52
	v_mul_f32_e32 v99, 0xbfb8aa3b, v53
	v_exp_f32_e32 v96, v96
	v_exp_f32_e32 v97, v97
	v_exp_f32_e32 v98, v98
	v_exp_f32_e32 v99, v99
	v_pk_fma_f32 v[84:85], v[34:35], v[92:93], v[84:85]
	v_add_f32_e32 v3, 1.0, v3
	v_mul_f32_e32 v111, 0xbfb8aa3b, v84
	v_add_f32_e32 v47, 1.0, v47
	v_mul_f32_e32 v108, 0xbfb8aa3b, v82
	v_add_f32_e32 v110, 1.0, v96
	v_add_f32_e32 v112, 1.0, v97
	v_rcp_f32_e32 v96, v3
	v_rcp_f32_e32 v97, v47
	v_exp_f32_e32 v3, v111
	v_mul_f32_e32 v47, 0xbfb8aa3b, v85
	v_exp_f32_e32 v108, v108
	v_add_f32_e32 v113, 1.0, v98
	v_add_f32_e32 v114, 1.0, v99
	v_rcp_f32_e32 v98, v110
	v_rcp_f32_e32 v99, v112
	v_exp_f32_e32 v47, v47
	v_add_f32_e32 v3, 1.0, v3
	v_add_f32_e32 v115, 1.0, v108
	v_rcp_f32_e32 v108, v113
	v_pk_mul_f32 v[112:113], v[48:49], v[96:97]
	v_pk_mul_f32 v[38:39], v[38:39], v[98:99]
	v_rcp_f32_e32 v48, v3
	v_add_f32_e32 v3, 1.0, v47
	v_lshlrev_b32_e32 v98, 16, v46
	v_and_b32_e32 v99, 0xffff0000, v46
	v_pk_fma_f32 v[46:47], v[20:21], v[94:95], 0 op_sel_hi:[1,1,0]
	v_rcp_f32_e32 v49, v3
	v_pk_fma_f32 v[46:47], v[24:25], v[78:79], v[46:47]
	v_pk_fma_f32 v[50:51], v[10:11], v[80:81], v[50:51]
	v_pk_fma_f32 v[46:47], v[28:29], v[88:89], v[46:47]
	v_pk_mul_f32 v[48:49], v[84:85], v[48:49]
	v_pk_fma_f32 v[46:47], v[32:33], v[98:99], v[46:47]
	v_lshlrev_b32_e32 v96, 16, v45
	v_mul_f32_e32 v3, 0xbfb8aa3b, v46
	v_exp_f32_e32 v3, v3
	v_mul_f32_e32 v84, 0xbfb8aa3b, v47
	v_exp_f32_e32 v95, v84
	v_and_b32_e32 v97, 0xffff0000, v45
	v_add_f32_e32 v3, 1.0, v3
	v_pk_fma_f32 v[50:51], v[14:15], v[54:55], v[50:51]
	v_rcp_f32_e32 v94, v3
	v_add_f32_e32 v3, 1.0, v95
	v_pk_fma_f32 v[50:51], v[18:19], v[96:97], v[50:51]
	v_rcp_f32_e32 v95, v3
	v_mul_f32_e32 v3, 0xbfb8aa3b, v50
	v_exp_f32_e32 v3, v3
	v_mul_f32_e32 v45, 0xbfb8aa3b, v51
	v_exp_f32_e32 v45, v45
	v_pk_mul_f32 v[46:47], v[46:47], v[94:95]
	v_add_f32_e32 v3, 1.0, v3
	v_rcp_f32_e32 v118, v3
	v_add_f32_e32 v3, 1.0, v45
	v_lshlrev_b32_e32 v94, 16, v44
	v_and_b32_e32 v95, 0xffff0000, v44
	v_pk_fma_f32 v[44:45], v[4:5], v[100:101], 0 op_sel_hi:[1,1,0]
	v_mul_f32_e32 v109, 0xbfb8aa3b, v83
	v_pk_fma_f32 v[44:45], v[8:9], v[86:87], v[44:45]
	v_exp_f32_e32 v109, v109
	v_pk_fma_f32 v[44:45], v[12:13], v[36:37], v[44:45]
	v_rcp_f32_e32 v119, v3
	v_pk_fma_f32 v[100:101], v[16:17], v[94:95], v[44:45]
	v_add_f32_e32 v116, 1.0, v109
	v_mul_f32_e32 v44, 0xbfb8aa3b, v100
	v_exp_f32_e32 v44, v44
	v_mul_f32_e32 v45, 0xbfb8aa3b, v101
	v_exp_f32_e32 v45, v45
	v_rcp_f32_e32 v110, v115
	v_add_f32_e32 v3, 1.0, v44
	v_rcp_f32_e32 v120, v3
	v_add_f32_e32 v3, 1.0, v45
	v_rcp_f32_e32 v111, v116
	v_rcp_f32_e32 v121, v3
	v_rcp_f32_e32 v109, v114
	v_pk_mul_f32 v[44:45], v[50:51], v[118:119]
	v_pk_mul_f32 v[82:83], v[82:83], v[110:111]
	v_pk_mul_f32 v[50:51], v[100:101], v[120:121]
	v_pk_mul_f32 v[114:115], v[52:53], v[108:109]
	v_pk_mul_f32 v[110:111], v[82:83], v[82:83]
	v_pk_mul_f32 v[100:101], v[50:51], v[50:51]
	v_pk_mul_f32 v[116:117], v[114:115], v[114:115]
	v_pk_mul_f32 v[118:119], v[44:45], v[44:45]
	v_mov_b32_e32 v120, v100
	v_mov_b32_e32 v121, v110
	v_mov_b32_e32 v110, v101
	v_pk_add_f32 v[100:101], v[120:121], v[110:111]
	v_mov_b32_e32 v110, v118
	v_mov_b32_e32 v111, v116
	v_pk_mul_f32 v[108:109], v[38:39], v[38:39]
	v_pk_mul_f32 v[122:123], v[46:47], v[46:47]
	v_pk_add_f32 v[100:101], v[110:111], v[100:101]
	v_mov_b32_e32 v116, v119
	v_pk_add_f32 v[100:101], v[116:117], v[100:101]
	v_mov_b32_e32 v110, v122
	v_mov_b32_e32 v111, v108
	v_pk_mul_f32 v[52:53], v[112:113], v[112:113]
	v_pk_mul_f32 v[84:85], v[48:49], v[48:49]
	v_pk_add_f32 v[100:101], v[110:111], v[100:101]
	v_mov_b32_e32 v108, v123
	v_pk_add_f32 v[100:101], v[108:109], v[100:101]
	v_mov_b32_e32 v108, v84
	v_mov_b32_e32 v109, v52
	v_pk_add_f32 v[100:101], v[108:109], v[100:101]
	v_mov_b64_e32 v[108:109], v[184:185]
	v_mov_b64_e32 v[110:111], v[186:187]
	v_mov_b32_e32 v52, v85
	v_pk_add_f32 v[52:53], v[52:53], v[100:101]
	ds_bpermute_b32 v85, v103, v53
	ds_bpermute_b32 v84, v103, v52
	s_waitcnt vmcnt(1)
	v_lshlrev_b32_e32 v116, 16, v42
	v_and_b32_e32 v117, 0xffff0000, v42
	v_pk_fma_f32 v[80:81], v[6:7], v[80:81], 0 op_sel_hi:[1,1,0]
	v_pk_fma_f32 v[6:7], v[6:7], v[54:55], 0 op_sel_hi:[1,1,0]
	s_waitcnt lgkmcnt(0)
	v_pk_add_f32 v[52:53], v[52:53], v[84:85]
	ds_bpermute_b32 v85, v104, v53
	ds_bpermute_b32 v84, v104, v52
	v_pk_fma_f32 v[80:81], v[10:11], v[54:55], v[80:81]
	v_pk_fma_f32 v[6:7], v[10:11], v[96:97], v[6:7]
	v_pk_fma_f32 v[80:81], v[14:15], v[96:97], v[80:81]
	s_waitcnt lgkmcnt(0)
	v_pk_add_f32 v[52:53], v[52:53], v[84:85]
	ds_bpermute_b32 v85, v105, v53
	ds_bpermute_b32 v84, v105, v52
	s_waitcnt lgkmcnt(0)
	v_pk_add_f32 v[52:53], v[52:53], v[84:85]
	ds_bpermute_b32 v85, v106, v53
	ds_bpermute_b32 v84, v106, v52
	s_waitcnt lgkmcnt(0)
	v_pk_add_f32 v[52:53], v[52:53], v[84:85]
	s_nop 0
	v_pk_add_f32 v[52:53], v[52:53], s[44:45] op_sel_hi:[1,0]
	s_waitcnt vmcnt(0)
	v_lshlrev_b32_e32 v10, 16, v109
	v_mul_f32_e32 v3, 0x4b800000, v53
	v_cmp_gt_f32_e32 vcc, s65, v53
	v_and_b32_e32 v11, 0xffff0000, v109
	s_nop 0
	v_cndmask_b32_e32 v3, v53, v3, vcc
	v_rsq_f32_e32 v3, v3
	v_mul_u32_u24_e32 v53, 0x440, v142
	v_mul_f32_e32 v84, 0x45800000, v3
	v_cndmask_b32_e32 v84, v3, v84, vcc
	v_pk_mul_f32 v[100:101], v[82:83], v[84:85] op_sel_hi:[1,0]
	v_pk_mul_f32 v[82:83], v[38:39], v[84:85] op_sel_hi:[1,0]
	v_pk_fma_f32 v[38:39], v[22:23], v[76:77], 0 op_sel_hi:[1,1,0]
	v_pk_mul_f32 v[114:115], v[114:115], v[84:85] op_sel_hi:[1,0]
	v_pk_fma_f32 v[38:39], v[26:27], v[90:91], v[38:39]
	v_pk_mul_f32 v[84:85], v[112:113], v[84:85] op_sel_hi:[1,0]
	v_lshlrev_b32_e32 v112, 16, v43
	v_and_b32_e32 v113, 0xffff0000, v43
	v_pk_fma_f32 v[38:39], v[30:31], v[92:93], v[38:39]
	v_pk_fma_f32 v[42:43], v[20:21], v[78:79], 0 op_sel_hi:[1,1,0]
	v_pk_fma_f32 v[76:77], v[34:35], v[112:113], v[38:39]
	v_pk_fma_f32 v[42:43], v[24:25], v[88:89], v[42:43]
	v_mul_f32_e32 v3, 0xbfb8aa3b, v76
	v_exp_f32_e32 v3, v3
	v_mul_f32_e32 v38, 0xbfb8aa3b, v77
	v_exp_f32_e32 v39, v38
	v_pk_fma_f32 v[42:43], v[28:29], v[98:99], v[42:43]
	v_add_f32_e32 v3, 1.0, v3
	v_pk_fma_f32 v[118:119], v[32:33], v[116:117], v[42:43]
	v_cvt_pk_bf16_f32 v38, v100, v101
	v_rcp_f32_e32 v100, v3
	v_add_f32_e32 v3, 1.0, v39
	v_mul_f32_e32 v39, 0xbfb8aa3b, v118
	v_exp_f32_e32 v39, v39
	v_mul_f32_e32 v42, 0xbfb8aa3b, v119
	v_exp_f32_e32 v42, v42
	v_rcp_f32_e32 v101, v3
	v_add_f32_e32 v3, 1.0, v39
	v_cvt_pk_bf16_f32 v39, v114, v115
	v_lshlrev_b32_e32 v114, 16, v41
	v_and_b32_e32 v115, 0xffff0000, v41
	v_rcp_f32_e32 v120, v3
	v_add_f32_e32 v3, 1.0, v42
	v_pk_fma_f32 v[80:81], v[18:19], v[114:115], v[80:81]
	v_rcp_f32_e32 v121, v3
	v_mul_f32_e32 v3, 0xbfb8aa3b, v80
	v_exp_f32_e32 v3, v3
	v_mul_f32_e32 v41, 0xbfb8aa3b, v81
	v_exp_f32_e32 v41, v41
	v_pk_mul_f32 v[42:43], v[76:77], v[100:101]
	v_add_f32_e32 v3, 1.0, v3
	v_pk_mul_f32 v[76:77], v[118:119], v[120:121]
	v_rcp_f32_e32 v118, v3
	v_add_f32_e32 v3, 1.0, v41
	v_lshlrev_b32_e32 v120, 16, v40
	v_and_b32_e32 v121, 0xffff0000, v40
	v_pk_fma_f32 v[40:41], v[4:5], v[86:87], 0 op_sel_hi:[1,1,0]
	v_pk_fma_f32 v[22:23], v[22:23], v[90:91], 0 op_sel_hi:[1,1,0]
	v_pk_fma_f32 v[40:41], v[8:9], v[36:37], v[40:41]
	v_pk_fma_f32 v[22:23], v[26:27], v[92:93], v[22:23]
	v_pk_fma_f32 v[40:41], v[12:13], v[94:95], v[40:41]
	v_rcp_f32_e32 v119, v3
	v_pk_fma_f32 v[40:41], v[16:17], v[120:121], v[40:41]
	v_pk_fma_f32 v[22:23], v[30:31], v[112:113], v[22:23]
	v_mul_f32_e32 v3, 0xbfb8aa3b, v40
	v_lshlrev_b32_e32 v26, 16, v111
	v_and_b32_e32 v27, 0xffff0000, v111
	v_exp_f32_e32 v3, v3
	v_mul_f32_e32 v86, 0xbfb8aa3b, v41
	v_pk_fma_f32 v[22:23], v[34:35], v[26:27], v[22:23]
	v_exp_f32_e32 v87, v86
	v_mul_f32_e32 v26, 0xbfb8aa3b, v22
	v_exp_f32_e32 v26, v26
	v_mul_f32_e32 v27, 0xbfb8aa3b, v23
	v_exp_f32_e32 v27, v27
	v_add_f32_e32 v3, 1.0, v3
	v_rcp_f32_e32 v86, v3
	v_add_f32_e32 v3, 1.0, v87
	v_rcp_f32_e32 v87, v3
	v_add_f32_e32 v3, 1.0, v26
	v_rcp_f32_e32 v26, v3
	v_add_f32_e32 v3, 1.0, v27
	v_rcp_f32_e32 v27, v3
	v_pk_fma_f32 v[20:21], v[20:21], v[88:89], 0 op_sel_hi:[1,1,0]
	v_pk_mul_f32 v[90:91], v[40:41], v[86:87]
	v_pk_fma_f32 v[20:21], v[24:25], v[98:99], v[20:21]
	v_pk_mul_f32 v[86:87], v[22:23], v[26:27]
	v_pk_fma_f32 v[20:21], v[28:29], v[116:117], v[20:21]
	v_lshlrev_b32_e32 v22, 16, v110
	v_and_b32_e32 v23, 0xffff0000, v110
	v_pk_fma_f32 v[20:21], v[32:33], v[22:23], v[20:21]
	v_pk_fma_f32 v[6:7], v[14:15], v[114:115], v[6:7]
	v_mul_f32_e32 v3, 0xbfb8aa3b, v20
	v_exp_f32_e32 v3, v3
	v_mul_f32_e32 v22, 0xbfb8aa3b, v21
	v_exp_f32_e32 v23, v22
	v_pk_fma_f32 v[4:5], v[4:5], v[36:37], 0 op_sel_hi:[1,1,0]
	v_add_f32_e32 v3, 1.0, v3
	v_rcp_f32_e32 v22, v3
	v_add_f32_e32 v3, 1.0, v23
	v_pk_fma_f32 v[6:7], v[18:19], v[10:11], v[6:7]
	v_pk_fma_f32 v[4:5], v[8:9], v[94:95], v[4:5]
	v_rcp_f32_e32 v23, v3
	v_mul_f32_e32 v3, 0xbfb8aa3b, v6
	v_pk_fma_f32 v[4:5], v[12:13], v[120:121], v[4:5]
	v_lshlrev_b32_e32 v8, 16, v108
	v_and_b32_e32 v9, 0xffff0000, v108
	v_exp_f32_e32 v3, v3
	v_mul_f32_e32 v10, 0xbfb8aa3b, v7
	v_pk_fma_f32 v[4:5], v[16:17], v[8:9], v[4:5]
	v_exp_f32_e32 v11, v10
	v_mul_f32_e32 v8, 0xbfb8aa3b, v4
	v_exp_f32_e32 v8, v8
	v_mul_f32_e32 v9, 0xbfb8aa3b, v5
	v_exp_f32_e32 v9, v9
	v_add_f32_e32 v3, 1.0, v3
	v_rcp_f32_e32 v10, v3
	v_add_f32_e32 v3, 1.0, v11
	v_rcp_f32_e32 v11, v3
	v_add_f32_e32 v3, 1.0, v8
	v_rcp_f32_e32 v8, v3
	v_add_f32_e32 v3, 1.0, v9
	v_rcp_f32_e32 v9, v3
	v_add_co_u32_e32 v12, vcc, 0x2000, v66
	v_pk_mul_f32 v[80:81], v[80:81], v[118:119]
	v_pk_mul_f32 v[4:5], v[4:5], v[8:9]
	v_addc_co_u32_e32 v13, vcc, 0, v67, vcc
	v_pk_mul_f32 v[30:31], v[90:91], v[90:91]
	v_pk_mul_f32 v[94:95], v[6:7], v[10:11]
	v_pk_mul_f32 v[6:7], v[4:5], v[4:5]
	v_add_co_u32_e32 v16, vcc, 0x4000, v66
	v_pk_mul_f32 v[92:93], v[80:81], v[80:81]
	v_pk_mul_f32 v[96:97], v[94:95], v[94:95]
	v_mov_b32_e32 v8, v6
	v_mov_b32_e32 v9, v30
	v_mov_b32_e32 v30, v7
	v_addc_co_u32_e32 v17, vcc, 0, v67, vcc
	v_pk_mul_f32 v[54:55], v[20:21], v[22:23]
	v_pk_add_f32 v[6:7], v[8:9], v[30:31]
	v_mov_b32_e32 v8, v96
	v_mov_b32_e32 v9, v92
	v_add_co_u32_e32 v20, vcc, 0x5000, v66
	v_pk_add_f32 v[98:99], v[8:9], v[6:7]
	v_lshl_add_u64 v[6:7], v[66:67], 0, s[52:53]
	v_lshl_add_u64 v[10:11], v[66:67], 0, s[54:55]
	v_lshl_add_u64 v[14:15], v[66:67], 0, s[56:57]
	v_lshl_add_u64 v[18:19], v[66:67], 0, s[58:59]
	v_addc_co_u32_e32 v21, vcc, 0, v67, vcc
	global_load_dwordx4 v[22:25], v[68:69], off
	s_nop 0
	global_load_dwordx4 v[6:9], v[6:7], off offset:16
	s_nop 0
	global_load_dwordx4 v[26:29], v[12:13], off offset:2048
	s_nop 0
	global_load_dwordx4 v[10:13], v[10:11], off offset:16
	s_nop 0
	global_load_dwordx4 v[30:33], v[16:17], off
	s_nop 0
	global_load_dwordx4 v[14:17], v[14:15], off offset:16
	s_nop 0
	global_load_dwordx4 v[34:37], v[20:21], off offset:2048
	s_nop 0
	global_load_dwordx4 v[18:21], v[18:19], off offset:16
	v_pk_mul_f32 v[100:101], v[76:77], v[76:77]
	v_pk_mul_f32 v[88:89], v[54:55], v[54:55]
	v_mov_b32_e32 v92, v97
	v_pk_add_f32 v[66:67], v[92:93], v[98:99]
	v_mov_b32_e32 v68, v88
	v_mov_b32_e32 v69, v100
	v_pk_mul_f32 v[78:79], v[42:43], v[42:43]
	v_pk_mul_f32 v[40:41], v[86:87], v[86:87]
	v_pk_add_f32 v[66:67], v[68:69], v[66:67]
	v_mov_b32_e32 v100, v89
	v_pk_add_f32 v[66:67], v[100:101], v[66:67]
	v_mov_b32_e32 v68, v40
	v_mov_b32_e32 v69, v78
	v_pk_add_f32 v[66:67], v[68:69], v[66:67]
	v_mov_b32_e32 v78, v41
	v_pk_add_f32 v[66:67], v[78:79], v[66:67]
	ds_bpermute_b32 v69, v103, v67
	ds_bpermute_b32 v68, v103, v66
	v_cvt_pk_bf16_f32 v40, v82, v83
	v_cvt_pk_bf16_f32 v41, v84, v85
	v_add_u32_e32 v78, v107, v53
	ds_write_b128 v78, v[38:41]
	s_waitcnt lgkmcnt(1)
	v_pk_add_f32 v[38:39], v[66:67], v[68:69]
	ds_bpermute_b32 v41, v104, v39
	ds_bpermute_b32 v40, v104, v38
	v_mul_f32_e32 v3, 0x4b800000, v52
	v_cmp_gt_f32_e32 vcc, s65, v52
	s_waitcnt lgkmcnt(0)
	v_pk_add_f32 v[38:39], v[38:39], v[40:41]
	ds_bpermute_b32 v41, v105, v39
	ds_bpermute_b32 v40, v105, v38
	v_cndmask_b32_e32 v3, v52, v3, vcc
	v_rsq_f32_e32 v3, v3
	s_waitcnt lgkmcnt(0)
	v_pk_add_f32 v[40:41], v[38:39], v[40:41]
	ds_bpermute_b32 v67, v106, v41
	ds_bpermute_b32 v66, v106, v40
	v_mul_f32_e32 v52, 0x45800000, v3
	v_cndmask_b32_e32 v52, v3, v52, vcc
	v_pk_mul_f32 v[44:45], v[44:45], v[52:53] op_sel_hi:[1,0]
	v_pk_mul_f32 v[50:51], v[50:51], v[52:53] op_sel_hi:[1,0]
	s_waitcnt lgkmcnt(0)
	v_pk_add_f32 v[40:41], v[40:41], v[66:67]
	v_cvt_pk_bf16_f32 v39, v44, v45
	v_pk_add_f32 v[44:45], v[40:41], s[44:45] op_sel_hi:[1,0]
	v_pk_mul_f32 v[46:47], v[46:47], v[52:53] op_sel_hi:[1,0]
	v_mul_f32_e32 v3, 0x4b800000, v45
	v_cmp_gt_f32_e32 vcc, s65, v45
	v_pk_mul_f32 v[48:49], v[48:49], v[52:53] op_sel_hi:[1,0]
	v_cvt_pk_bf16_f32 v38, v50, v51
	v_cndmask_b32_e32 v3, v45, v3, vcc
	v_rsq_f32_e32 v3, v3
	v_cvt_pk_bf16_f32 v40, v46, v47
	v_cvt_pk_bf16_f32 v41, v48, v49
	ds_write_b128 v78, v[38:41] offset:272
	v_mul_f32_e32 v38, 0x45800000, v3
	v_cndmask_b32_e32 v38, v3, v38, vcc
	v_mul_f32_e32 v3, 0x4b800000, v44
	v_cmp_gt_f32_e32 vcc, s65, v44
	v_pk_mul_f32 v[40:41], v[90:91], v[38:39] op_sel_hi:[1,0]
	v_pk_mul_f32 v[46:47], v[80:81], v[38:39] op_sel_hi:[1,0]
	v_cndmask_b32_e32 v3, v44, v3, vcc
	v_rsq_f32_e32 v3, v3
	v_pk_mul_f32 v[48:49], v[76:77], v[38:39] op_sel_hi:[1,0]
	v_pk_mul_f32 v[42:43], v[42:43], v[38:39] op_sel_hi:[1,0]
	v_cvt_pk_bf16_f32 v38, v40, v41
	v_cvt_pk_bf16_f32 v39, v46, v47
	v_cvt_pk_bf16_f32 v40, v48, v49
	v_cvt_pk_bf16_f32 v41, v42, v43
	ds_write_b128 v78, v[38:41] offset:544
	v_mul_f32_e32 v38, 0x45800000, v3
	v_cndmask_b32_e32 v38, v3, v38, vcc
	v_pk_mul_f32 v[4:5], v[4:5], v[38:39] op_sel_hi:[1,0]
	v_pk_mul_f32 v[40:41], v[94:95], v[38:39] op_sel_hi:[1,0]
	v_pk_mul_f32 v[42:43], v[54:55], v[38:39] op_sel_hi:[1,0]
	v_pk_mul_f32 v[44:45], v[86:87], v[38:39] op_sel_hi:[1,0]
	v_cvt_pk_bf16_f32 v38, v4, v5
	v_cvt_pk_bf16_f32 v39, v40, v41
	v_cvt_pk_bf16_f32 v40, v42, v43
	v_cvt_pk_bf16_f32 v41, v44, v45
	ds_write_b128 v78, v[38:41] offset:816
	v_add_u32_e32 v38, 0x400, v56
	v_ashrrev_i32_e32 v39, 31, v38
	v_mov_b32_e32 v3, 0
	v_mov_b32_e32 v4, 0
	v_mov_b32_e32 v5, 0
	s_and_saveexec_b64 s[60:61], s[2:3]
	s_cbranch_execz .LBB0_310
	v_mov_b64_e32 v[2:3], s[8:9]
	v_mad_i64_i32 v[2:3], s[0:1], v57, s45, v[2:3]
	v_lshl_add_u64 v[2:3], v[38:39], 1, v[2:3]
.LBB0_310:
	s_or_b64 exec, exec, s[60:61]
	v_mov_b32_e32 v54, 0
	v_mov_b32_e32 v50, 0
	v_mov_b32_e32 v51, 0
	v_mov_b32_e32 v52, 0
	v_mov_b32_e32 v53, 0
	s_and_saveexec_b64 s[60:61], s[4:5]
	s_cbranch_execz .LBB0_312
	v_mov_b64_e32 v[40:41], s[8:9]
	v_mad_i64_i32 v[40:41], s[0:1], v63, s45, v[40:41]
	v_lshl_add_u64 v[40:41], v[38:39], 1, v[40:41]
.LBB0_312:
	s_or_b64 exec, exec, s[60:61]
	v_mov_b32_e32 v55, 0
	v_mov_b32_e32 v56, 0
	v_mov_b32_e32 v57, 0
	s_and_saveexec_b64 s[4:5], s[2:3]
	s_cbranch_execz .LBB0_314
	v_mov_b64_e32 v[40:41], s[8:9]
	v_mad_i64_i32 v[40:41], s[0:1], v61, s45, v[40:41]
	v_lshl_add_u64 v[38:39], v[38:39], 1, v[40:41]
.LBB0_314:
	s_or_b64 exec, exec, s[4:5]
	s_waitcnt vmcnt(0)
	v_mov_b64_e32 v[2:3], v[188:189]
	v_mov_b64_e32 v[4:5], v[190:191]
	v_mov_b64_e32 v[50:51], v[192:193]
	v_mov_b64_e32 v[52:53], v[194:195]
	v_mov_b64_e32 v[54:55], v[196:197]
	v_mov_b64_e32 v[56:57], v[198:199]
	v_mov_b64_e32 v[80:81], v[200:201]
	v_mov_b64_e32 v[82:83], v[202:203]
	v_mov_b64_e32 v[46:47], v[204:205]
	v_mov_b64_e32 v[48:49], v[206:207]
	v_mov_b64_e32 v[42:43], v[208:209]
	v_mov_b64_e32 v[44:45], v[210:211]
	v_mov_b64_e32 v[38:39], v[212:213]
	v_mov_b64_e32 v[40:41], v[214:215]
	v_lshlrev_b32_e32 v70, 16, v2
	v_and_b32_e32 v71, 0xffff0000, v2
	v_lshlrev_b32_e32 v74, 16, v50
	v_and_b32_e32 v75, 0xffff0000, v50
	v_lshlrev_b32_e32 v2, 16, v3
	v_and_b32_e32 v3, 0xffff0000, v3
	v_lshlrev_b32_e32 v84, 16, v51
	v_and_b32_e32 v85, 0xffff0000, v51
	v_lshlrev_b32_e32 v50, 16, v4
	v_and_b32_e32 v51, 0xffff0000, v4
	v_lshlrev_b32_e32 v4, 16, v5
	v_and_b32_e32 v5, 0xffff0000, v5
	v_lshlrev_b32_e32 v86, 16, v52
	v_and_b32_e32 v87, 0xffff0000, v52
	v_lshlrev_b32_e32 v88, 16, v53
	v_and_b32_e32 v89, 0xffff0000, v53
	v_pk_fma_f32 v[52:53], v[22:23], v[70:71], 0 op_sel_hi:[1,1,0]
	v_pk_fma_f32 v[2:3], v[24:25], v[2:3], 0 op_sel_hi:[1,1,0]
	v_pk_fma_f32 v[50:51], v[6:7], v[50:51], 0 op_sel_hi:[1,1,0]
	v_pk_fma_f32 v[4:5], v[8:9], v[4:5], 0 op_sel_hi:[1,1,0]
	v_lshlrev_b32_e32 v64, 16, v54
	v_and_b32_e32 v65, 0xffff0000, v54
	v_lshlrev_b32_e32 v54, 16, v55
	v_and_b32_e32 v55, 0xffff0000, v55
	v_lshlrev_b32_e32 v66, 16, v56
	v_and_b32_e32 v67, 0xffff0000, v56
	v_lshlrev_b32_e32 v56, 16, v57
	v_and_b32_e32 v57, 0xffff0000, v57
	v_pk_fma_f32 v[52:53], v[26:27], v[74:75], v[52:53]
	v_pk_fma_f32 v[2:3], v[28:29], v[84:85], v[2:3]
	v_pk_fma_f32 v[50:51], v[10:11], v[86:87], v[50:51]
	v_pk_fma_f32 v[4:5], v[12:13], v[88:89], v[4:5]
	v_pk_fma_f32 v[70:71], v[30:31], v[64:65], v[52:53]
	v_pk_fma_f32 v[72:73], v[32:33], v[54:55], v[2:3]
	v_pk_fma_f32 v[90:91], v[14:15], v[66:67], v[50:51]
	v_pk_fma_f32 v[92:93], v[16:17], v[56:57], v[4:5]
	v_pk_fma_f32 v[74:75], v[22:23], v[74:75], 0 op_sel_hi:[1,1,0]
	v_pk_fma_f32 v[86:87], v[6:7], v[86:87], 0 op_sel_hi:[1,1,0]
	v_pk_fma_f32 v[74:75], v[26:27], v[64:65], v[74:75]
	v_pk_fma_f32 v[86:87], v[10:11], v[66:67], v[86:87]
	v_pk_fma_f32 v[88:89], v[8:9], v[88:89], 0 op_sel_hi:[1,1,0]
	v_pk_fma_f32 v[64:65], v[22:23], v[64:65], 0 op_sel_hi:[1,1,0]
	v_pk_fma_f32 v[88:89], v[12:13], v[56:57], v[88:89]
	v_pk_fma_f32 v[66:67], v[6:7], v[66:67], 0 op_sel_hi:[1,1,0]
	v_pk_fma_f32 v[56:57], v[8:9], v[56:57], 0 op_sel_hi:[1,1,0]
	s_lshl_b32 s0, s89, 8
	v_and_b32_e32 v68, 0xff, v143
	v_lshl_add_u32 v61, v62, 6, s0
	v_and_b32_e32 v76, 63, v143
	v_add_u32_e32 v69, 0x12d00, v140
	v_cmp_gt_u32_e32 vcc, 64, v68
	s_waitcnt vmcnt(3)
	v_lshlrev_b32_e32 v52, 16, v80
	v_and_b32_e32 v53, 0xffff0000, v80
	v_lshlrev_b32_e32 v50, 16, v81
	v_and_b32_e32 v51, 0xffff0000, v81
	v_lshlrev_b32_e32 v4, 16, v82
	v_and_b32_e32 v5, 0xffff0000, v82
	v_lshlrev_b32_e32 v2, 16, v83
	v_and_b32_e32 v3, 0xffff0000, v83
	v_pk_fma_f32 v[70:71], v[34:35], v[52:53], v[70:71]
	v_pk_fma_f32 v[72:73], v[36:37], v[50:51], v[72:73]
	v_pk_fma_f32 v[80:81], v[18:19], v[4:5], v[90:91]
	v_pk_fma_f32 v[82:83], v[20:21], v[2:3], v[92:93]
	v_mul_f32_e32 v63, 0xbfb8aa3b, v70
	v_mul_f32_e32 v77, 0xbfb8aa3b, v71
	v_mul_f32_e32 v79, 0xbfb8aa3b, v72
	v_mul_f32_e32 v90, 0xbfb8aa3b, v73
	v_mul_f32_e32 v91, 0xbfb8aa3b, v80
	v_mul_f32_e32 v92, 0xbfb8aa3b, v81
	v_mul_f32_e32 v93, 0xbfb8aa3b, v82
	v_mul_f32_e32 v94, 0xbfb8aa3b, v83
	v_exp_f32_e32 v63, v63
	v_exp_f32_e32 v77, v77
	v_exp_f32_e32 v79, v79
	v_exp_f32_e32 v90, v90
	v_exp_f32_e32 v91, v91
	v_exp_f32_e32 v92, v92
	v_exp_f32_e32 v93, v93
	v_exp_f32_e32 v94, v94
	v_add_f32_e32 v63, 1.0, v63
	v_add_f32_e32 v77, 1.0, v77
	v_add_f32_e32 v79, 1.0, v79
	v_add_f32_e32 v95, 1.0, v90
	v_add_f32_e32 v96, 1.0, v91
	v_add_f32_e32 v97, 1.0, v92
	v_add_f32_e32 v98, 1.0, v93
	v_add_f32_e32 v99, 1.0, v94
	v_rcp_f32_e32 v90, v63
	v_rcp_f32_e32 v91, v77
	v_rcp_f32_e32 v92, v79
	v_rcp_f32_e32 v93, v95
	v_rcp_f32_e32 v94, v96
	v_rcp_f32_e32 v95, v97
	v_rcp_f32_e32 v96, v98
	v_rcp_f32_e32 v97, v99
	v_pk_mul_f32 v[70:71], v[70:71], v[90:91]
	v_pk_mul_f32 v[72:73], v[72:73], v[92:93]
	v_pk_mul_f32 v[80:81], v[80:81], v[94:95]
	v_pk_mul_f32 v[82:83], v[82:83], v[96:97]
	v_cvt_pk_bf16_f32 v70, v70, v71
	v_cvt_pk_bf16_f32 v71, v72, v73
	v_cvt_pk_bf16_f32 v72, v80, v81
	v_cvt_pk_bf16_f32 v73, v82, v83
	ds_write_b128 v78, v[70:73] offset:34816
	v_pk_fma_f32 v[72:73], v[24:25], v[84:85], 0 op_sel_hi:[1,1,0]
	s_waitcnt vmcnt(2)
	v_lshlrev_b32_e32 v80, 16, v46
	v_and_b32_e32 v81, 0xffff0000, v46
	v_pk_fma_f32 v[74:75], v[30:31], v[52:53], v[74:75]
	v_pk_fma_f32 v[72:73], v[28:29], v[54:55], v[72:73]
	v_pk_fma_f32 v[74:75], v[34:35], v[80:81], v[74:75]
	v_lshlrev_b32_e32 v70, 16, v47
	v_and_b32_e32 v71, 0xffff0000, v47
	v_pk_fma_f32 v[72:73], v[32:33], v[50:51], v[72:73]
	v_mul_f32_e32 v63, 0xbfb8aa3b, v75
	v_pk_fma_f32 v[72:73], v[36:37], v[70:71], v[72:73]
	v_exp_f32_e32 v63, v63
	v_mul_f32_e32 v47, 0xbfb8aa3b, v72
	v_exp_f32_e32 v77, v47
	v_lshlrev_b32_e32 v84, 16, v48
	v_and_b32_e32 v85, 0xffff0000, v48
	v_pk_fma_f32 v[86:87], v[14:15], v[4:5], v[86:87]
	v_add_f32_e32 v63, 1.0, v63
	v_mul_f32_e32 v47, 0xbfb8aa3b, v73
	v_pk_fma_f32 v[86:87], v[18:19], v[84:85], v[86:87]
	v_exp_f32_e32 v79, v47
	v_rcp_f32_e32 v47, v63
	v_add_f32_e32 v63, 1.0, v77
	v_mul_f32_e32 v77, 0xbfb8aa3b, v87
	v_exp_f32_e32 v77, v77
	v_lshlrev_b32_e32 v90, 16, v49
	v_and_b32_e32 v91, 0xffff0000, v49
	v_pk_fma_f32 v[88:89], v[16:17], v[2:3], v[88:89]
	v_mul_f32_e32 v46, 0xbfb8aa3b, v74
	v_pk_fma_f32 v[88:89], v[20:21], v[90:91], v[88:89]
	v_rcp_f32_e32 v82, v63
	v_add_f32_e32 v63, 1.0, v79
	v_mul_f32_e32 v49, 0xbfb8aa3b, v88
	v_exp_f32_e32 v46, v46
	v_mul_f32_e32 v48, 0xbfb8aa3b, v86
	v_rcp_f32_e32 v83, v63
	v_add_f32_e32 v63, 1.0, v77
	v_exp_f32_e32 v77, v49
	v_mul_f32_e32 v49, 0xbfb8aa3b, v89
	v_exp_f32_e32 v48, v48
	v_exp_f32_e32 v79, v49
	v_add_f32_e32 v46, 1.0, v46
	v_rcp_f32_e32 v49, v63
	v_add_f32_e32 v63, 1.0, v77
	v_rcp_f32_e32 v46, v46
	v_add_f32_e32 v48, 1.0, v48
	v_rcp_f32_e32 v92, v63
	v_add_f32_e32 v63, 1.0, v79
	v_rcp_f32_e32 v48, v48
	v_rcp_f32_e32 v93, v63
	v_pk_mul_f32 v[46:47], v[74:75], v[46:47]
	v_pk_mul_f32 v[72:73], v[72:73], v[82:83]
	v_pk_fma_f32 v[64:65], v[26:27], v[52:53], v[64:65]
	v_pk_mul_f32 v[48:49], v[86:87], v[48:49]
	v_pk_mul_f32 v[74:75], v[88:89], v[92:93]
	v_cvt_pk_bf16_f32 v46, v46, v47
	v_cvt_pk_bf16_f32 v47, v72, v73
	v_pk_fma_f32 v[64:65], v[30:31], v[80:81], v[64:65]
	s_waitcnt vmcnt(1)
	v_lshlrev_b32_e32 v72, 16, v42
	v_and_b32_e32 v73, 0xffff0000, v42
	v_cvt_pk_bf16_f32 v48, v48, v49
	v_cvt_pk_bf16_f32 v49, v74, v75
	v_pk_fma_f32 v[64:65], v[34:35], v[72:73], v[64:65]
	ds_write_b128 v78, v[46:49] offset:35088
	v_mul_f32_e32 v63, 0xbfb8aa3b, v65
	v_pk_fma_f32 v[46:47], v[24:25], v[54:55], 0 op_sel_hi:[1,1,0]
	v_exp_f32_e32 v63, v63
	v_pk_fma_f32 v[46:47], v[28:29], v[50:51], v[46:47]
	v_lshlrev_b32_e32 v48, 16, v43
	v_pk_fma_f32 v[46:47], v[32:33], v[70:71], v[46:47]
	v_and_b32_e32 v49, 0xffff0000, v43
	v_pk_fma_f32 v[46:47], v[36:37], v[48:49], v[46:47]
	v_pk_fma_f32 v[66:67], v[10:11], v[4:5], v[66:67]
	v_mul_f32_e32 v43, 0xbfb8aa3b, v46
	v_pk_fma_f32 v[66:67], v[14:15], v[84:85], v[66:67]
	v_lshlrev_b32_e32 v74, 16, v44
	v_and_b32_e32 v75, 0xffff0000, v44
	v_pk_fma_f32 v[56:57], v[12:13], v[2:3], v[56:57]
	v_add_f32_e32 v63, 1.0, v63
	v_exp_f32_e32 v54, v43
	v_mul_f32_e32 v43, 0xbfb8aa3b, v47
	v_pk_fma_f32 v[66:67], v[18:19], v[74:75], v[66:67]
	v_pk_fma_f32 v[56:57], v[16:17], v[90:91], v[56:57]
	v_lshlrev_b32_e32 v82, 16, v45
	v_and_b32_e32 v83, 0xffff0000, v45
	v_pk_fma_f32 v[22:23], v[22:23], v[52:53], 0 op_sel_hi:[1,1,0]
	v_pk_fma_f32 v[24:25], v[24:25], v[50:51], 0 op_sel_hi:[1,1,0]
	v_pk_fma_f32 v[4:5], v[6:7], v[4:5], 0 op_sel_hi:[1,1,0]
	v_pk_fma_f32 v[2:3], v[8:9], v[2:3], 0 op_sel_hi:[1,1,0]
	v_exp_f32_e32 v55, v43
	v_rcp_f32_e32 v43, v63
	v_mul_f32_e32 v63, 0xbfb8aa3b, v67
	v_pk_fma_f32 v[56:57], v[20:21], v[82:83], v[56:57]
	v_pk_fma_f32 v[22:23], v[26:27], v[80:81], v[22:23]
	v_pk_fma_f32 v[24:25], v[28:29], v[70:71], v[24:25]
	v_pk_fma_f32 v[4:5], v[10:11], v[84:85], v[4:5]
	v_pk_fma_f32 v[2:3], v[12:13], v[90:91], v[2:3]
	v_exp_f32_e32 v63, v63
	v_mul_f32_e32 v45, 0xbfb8aa3b, v56
	v_pk_fma_f32 v[22:23], v[30:31], v[72:73], v[22:23]
	s_waitcnt vmcnt(0)
	v_lshlrev_b32_e32 v26, 16, v38
	v_and_b32_e32 v27, 0xffff0000, v38
	v_pk_fma_f32 v[24:25], v[32:33], v[48:49], v[24:25]
	v_lshlrev_b32_e32 v28, 16, v39
	v_and_b32_e32 v29, 0xffff0000, v39
	v_pk_fma_f32 v[4:5], v[14:15], v[74:75], v[4:5]
	v_lshlrev_b32_e32 v6, 16, v40
	v_and_b32_e32 v7, 0xffff0000, v40
	v_pk_fma_f32 v[2:3], v[16:17], v[82:83], v[2:3]
	v_lshlrev_b32_e32 v8, 16, v41
	v_and_b32_e32 v9, 0xffff0000, v41
	v_mul_f32_e32 v42, 0xbfb8aa3b, v64
	v_mul_f32_e32 v44, 0xbfb8aa3b, v66
	v_exp_f32_e32 v77, v45
	v_mul_f32_e32 v45, 0xbfb8aa3b, v57
	v_pk_fma_f32 v[22:23], v[34:35], v[26:27], v[22:23]
	v_pk_fma_f32 v[24:25], v[36:37], v[28:29], v[24:25]
	v_pk_fma_f32 v[4:5], v[18:19], v[6:7], v[4:5]
	v_pk_fma_f32 v[2:3], v[20:21], v[8:9], v[2:3]
	v_exp_f32_e32 v42, v42
	v_exp_f32_e32 v44, v44
	v_exp_f32_e32 v79, v45
	v_mul_f32_e32 v26, 0xbfb8aa3b, v22
	v_mul_f32_e32 v27, 0xbfb8aa3b, v23
	v_mul_f32_e32 v28, 0xbfb8aa3b, v24
	v_mul_f32_e32 v29, 0xbfb8aa3b, v25
	v_mul_f32_e32 v6, 0xbfb8aa3b, v4
	v_mul_f32_e32 v7, 0xbfb8aa3b, v5
	v_mul_f32_e32 v8, 0xbfb8aa3b, v2
	v_mul_f32_e32 v9, 0xbfb8aa3b, v3
	v_exp_f32_e32 v26, v26
	v_exp_f32_e32 v27, v27
	v_exp_f32_e32 v28, v28
	v_exp_f32_e32 v29, v29
	v_exp_f32_e32 v6, v6
	v_exp_f32_e32 v7, v7
	v_exp_f32_e32 v8, v8
	v_exp_f32_e32 v9, v9
	v_add_f32_e32 v63, 1.0, v63
	v_rcp_f32_e32 v45, v63
	v_add_f32_e32 v63, 1.0, v77
	v_add_f32_e32 v42, 1.0, v42
	v_add_f32_e32 v54, 1.0, v54
	v_add_f32_e32 v55, 1.0, v55
	v_add_f32_e32 v44, 1.0, v44
	v_rcp_f32_e32 v86, v63
	v_add_f32_e32 v63, 1.0, v79
	v_rcp_f32_e32 v42, v42
	v_rcp_f32_e32 v54, v54
	v_rcp_f32_e32 v55, v55
	v_rcp_f32_e32 v44, v44
	v_rcp_f32_e32 v87, v63
	v_add_f32_e32 v26, 1.0, v26
	v_add_f32_e32 v27, 1.0, v27
	v_add_f32_e32 v28, 1.0, v28
	v_add_f32_e32 v29, 1.0, v29
	v_add_f32_e32 v6, 1.0, v6
	v_add_f32_e32 v7, 1.0, v7
	v_add_f32_e32 v8, 1.0, v8
	v_add_f32_e32 v9, 1.0, v9
	v_rcp_f32_e32 v26, v26
	v_rcp_f32_e32 v27, v27
	v_rcp_f32_e32 v28, v28
	v_rcp_f32_e32 v29, v29
	v_rcp_f32_e32 v6, v6
	v_rcp_f32_e32 v7, v7
	v_rcp_f32_e32 v8, v8
	v_rcp_f32_e32 v9, v9
	v_pk_mul_f32 v[42:43], v[64:65], v[42:43]
	v_pk_mul_f32 v[46:47], v[46:47], v[54:55]
	v_pk_mul_f32 v[44:45], v[66:67], v[44:45]
	v_pk_mul_f32 v[54:55], v[56:57], v[86:87]
	v_cvt_pk_bf16_f32 v42, v42, v43
	v_cvt_pk_bf16_f32 v43, v46, v47
	v_cvt_pk_bf16_f32 v44, v44, v45
	v_cvt_pk_bf16_f32 v45, v54, v55
	v_pk_mul_f32 v[10:11], v[22:23], v[26:27]
	v_pk_mul_f32 v[12:13], v[24:25], v[28:29]
	v_pk_mul_f32 v[4:5], v[4:5], v[6:7]
	v_pk_mul_f32 v[6:7], v[2:3], v[8:9]
	ds_write_b128 v78, v[42:45] offset:35360
	v_cvt_pk_bf16_f32 v2, v10, v11
	v_cvt_pk_bf16_f32 v3, v12, v13
	v_cvt_pk_bf16_f32 v4, v4, v5
	v_cvt_pk_bf16_f32 v5, v6, v7
	v_or_b32_e32 v42, s87, v61
	v_add_u32_e32 v45, 0x12c00, v140
	v_add_u32_e32 v46, 0x12e00, v140
	ds_write_b128 v78, v[2:5] offset:35632
	s_and_saveexec_b64 s[2:3], vcc
	s_cbranch_execz .LBB0_319
	v_or_b32_e32 v2, s88, v68
	v_ashrrev_i32_e32 v3, 31, v2
	v_ashrrev_i32_e32 v63, 31, v62
	v_lshlrev_b64 v[2:3], 5, v[2:3]
	v_lshl_add_u64 v[2:3], s[22:23], 0, v[2:3]
	v_lshlrev_b64 v[4:5], 2, v[62:63]
	v_lshl_add_u64 v[2:3], v[2:3], 0, v[4:5]
	v_lshl_add_u64 v[6:7], s[20:21], 0, v[4:5]
	v_mov_b32_e32 v8, v126
	s_nop 0
	v_mov_b32_e32 v2, v127
	v_lshl_add_u64 v[4:5], s[14:15], 0, v[4:5]
	v_mov_b32_e32 v6, v128
	s_nop 0
	v_mov_b32_e32 v3, v129
	s_waitcnt vmcnt(1)
	v_add_f32_e32 v4, v8, v6
	v_cmp_nlt_f32_e32 vcc, s66, v4
	s_and_saveexec_b64 s[4:5], vcc
	s_cbranch_execz .LBB0_317
	v_mul_f32_e32 v5, 0x3fb8aa3b, v4
	v_rndne_f32_e32 v6, v5
	v_sub_f32_e32 v7, v5, v6
	v_fma_f32 v5, v4, s67, -v5
	v_fmac_f32_e32 v5, 0x32a5705f, v4
	v_add_f32_e32 v5, v7, v5
	v_cvt_i32_f32_e32 v6, v6
	v_exp_f32_e32 v5, v5
	v_cmp_ngt_f32_e32 vcc, s72, v4
	v_ldexp_f32 v5, v5, v6
	s_nop 0
	v_cndmask_b32_e32 v5, 0, v5, vcc
	v_cmp_nlt_f32_e32 vcc, s73, v4
	s_nop 1
	v_cndmask_b32_e32 v18, v138, v5, vcc
	v_add_f32_e32 v6, 1.0, v18
	v_add_f32_e32 v4, -1.0, v6
	v_sub_f32_e32 v5, v4, v6
	v_add_f32_e32 v5, 1.0, v5
	v_sub_f32_e32 v4, v18, v4
	v_add_f32_e32 v7, v4, v5
	v_frexp_mant_f32_e32 v8, v6
	v_cvt_f64_f32_e32 v[4:5], v6
	v_frexp_exp_i32_f64_e32 v4, v[4:5]
	v_cmp_gt_f32_e32 vcc, s75, v8
	s_nop 1
	v_subbrev_co_u32_e32 v12, vcc, 0, v4, vcc
	v_sub_u32_e32 v4, 0, v12
	v_ldexp_f32 v5, v6, v4
	v_add_f32_e32 v6, -1.0, v5
	v_add_f32_e32 v8, 1.0, v5
	v_ldexp_f32 v4, v7, v4
	v_add_f32_e32 v7, 1.0, v6
	v_add_f32_e32 v9, -1.0, v8
	v_sub_f32_e32 v7, v5, v7
	v_sub_f32_e32 v5, v5, v9
	v_add_f32_e32 v7, v4, v7
	v_add_f32_e32 v4, v4, v5
	v_add_f32_e32 v13, v8, v4
	v_rcp_f32_e32 v15, v13
	v_sub_f32_e32 v5, v8, v13
	v_add_f32_e32 v14, v4, v5
	v_add_f32_e32 v5, v6, v7
	v_mul_f32_e32 v17, v5, v15
	v_sub_f32_e32 v4, v6, v5
	v_mul_f32_e32 v6, v13, v17
	v_fma_f32 v8, v17, v13, -v6
	v_fmac_f32_e32 v8, v17, v14
	v_add_f32_e32 v16, v7, v4
	v_add_f32_e32 v4, v6, v8
	v_sub_f32_e32 v7, v5, v4
	v_pk_add_f32 v[10:11], v[4:5], v[6:7] neg_lo:[0,1] neg_hi:[0,1]
	v_mov_b32_e32 v9, v4
	v_pk_add_f32 v[4:5], v[10:11], v[8:9] neg_lo:[0,1] neg_hi:[0,1]
	v_cmp_neq_f32_e32 vcc, s74, v18
	v_add_f32_e32 v5, v16, v5
	v_add_f32_e32 v4, v4, v5
	v_add_f32_e32 v5, v7, v4
	v_mul_f32_e32 v16, v15, v5
	v_mul_f32_e32 v6, v13, v16
	v_fma_f32 v8, v16, v13, -v6
	v_fmac_f32_e32 v8, v16, v14
	v_sub_f32_e32 v7, v7, v5
	v_add_f32_e32 v13, v4, v7
	v_add_f32_e32 v4, v6, v8
	v_sub_f32_e32 v7, v5, v4
	v_pk_add_f32 v[10:11], v[4:5], v[6:7] neg_lo:[0,1] neg_hi:[0,1]
	v_mov_b32_e32 v9, v4
	v_pk_add_f32 v[4:5], v[10:11], v[8:9] neg_lo:[0,1] neg_hi:[0,1]
	s_nop 0
	v_add_f32_e32 v5, v13, v5
	v_add_f32_e32 v4, v4, v5
	v_add_f32_e32 v5, v17, v16
	v_add_f32_e32 v4, v7, v4
	v_sub_f32_e32 v6, v5, v17
	v_mul_f32_e32 v4, v15, v4
	v_sub_f32_e32 v6, v16, v6
	v_add_f32_e32 v6, v6, v4
	v_add_f32_e32 v8, v5, v6
	v_mul_f32_e32 v9, v8, v8
	v_fmamk_f32 v4, v9, 0x3e9b6dac, v136
	v_fmaak_f32 v61, v9, v4, 0x3f2aaada
	v_cvt_f32_i32_e32 v4, v12
	v_sub_f32_e32 v5, v8, v5
	v_sub_f32_e32 v5, v6, v5
	v_ldexp_f32 v10, v5, 1
	v_mul_f32_e32 v5, v8, v9
	v_ldexp_f32 v7, v8, 1
	v_pk_mul_f32 v[8:9], v[4:5], v[60:61]
	s_nop 0
	v_fma_f32 v6, v4, s76, -v8
	v_fmac_f32_e32 v6, 0xb102e308, v4
	v_pk_add_f32 v[4:5], v[8:9], v[6:7]
	s_nop 0
	v_sub_f32_e32 v7, v5, v7
	v_sub_f32_e32 v7, v9, v7
	v_add_f32_e32 v11, v10, v7
	v_mov_b32_e32 v10, v8
	v_pk_add_f32 v[8:9], v[4:5], v[8:9] neg_lo:[0,1] neg_hi:[0,1]
	v_pk_add_f32 v[12:13], v[4:5], v[10:11]
	v_mov_b32_e32 v7, v4
	v_mov_b32_e32 v9, v13
	v_pk_add_f32 v[14:15], v[6:7], v[8:9] neg_lo:[0,1] neg_hi:[0,1]
	v_pk_add_f32 v[6:7], v[6:7], v[8:9]
	v_mov_b32_e32 v10, v11
	v_pk_add_f32 v[8:9], v[6:7], v[4:5] op_sel:[1,0] op_sel_hi:[0,1] neg_lo:[0,1] neg_hi:[0,1]
	v_pk_add_f32 v[16:17], v[12:13], v[8:9] op_sel_hi:[1,0] neg_lo:[0,1] neg_hi:[0,1]
	v_mov_b32_e32 v12, v13
	v_mov_b32_e32 v13, v7
	v_pk_mov_b32 v[8:9], v[4:5], v[8:9] op_sel:[1,0]
	v_mov_b32_e32 v11, v4
	v_pk_add_f32 v[8:9], v[12:13], v[8:9] neg_lo:[0,1] neg_hi:[0,1]
	v_mov_b32_e32 v16, v14
	v_pk_add_f32 v[4:5], v[10:11], v[8:9] neg_lo:[0,1] neg_hi:[0,1]
	v_mov_b32_e32 v15, v7
	v_pk_add_f32 v[8:9], v[16:17], v[4:5]
	s_nop 0
	v_pk_add_f32 v[10:11], v[8:9], v[8:9] op_sel:[0,1] op_sel_hi:[1,0]
	s_nop 0
	v_pk_add_f32 v[6:7], v[6:7], v[10:11] op_sel:[1,0] op_sel_hi:[0,1]
	v_mov_b32_e32 v9, v6
	v_pk_add_f32 v[12:13], v[8:9], v[14:15] neg_lo:[0,1] neg_hi:[0,1]
	v_mov_b32_e32 v5, v10
	v_sub_f32_e32 v7, v8, v12
	v_pk_add_f32 v[4:5], v[4:5], v[12:13] neg_lo:[0,1] neg_hi:[0,1]
	v_sub_f32_e32 v7, v14, v7
	v_add_f32_e32 v4, v4, v7
	v_add_f32_e32 v4, v4, v5
	v_add_f32_e32 v4, v6, v4
	v_cndmask_b32_e32 v4, v138, v4, vcc
	v_cmp_lt_f32_e64 vcc, |v18|, s77
	s_nop 1
	v_cndmask_b32_e32 v4, v4, v18, vcc
